# stack15 + fox-attention steady loop: fourteen QK-phase lgkmcnt waits already covered by the closing lgkmcnt(0) before each step barrier removed
# baseline (speedup 1.0000x reference)
.LBB0_251:
	v_add_u32_e32 v0, s18, v225
	ds_read_b64_tr_b16 v[192:193], v0 offset:24576
	ds_read_b64_tr_b16 v[194:195], v0 offset:25088
	v_add_f32_e32 v2, v80, v81
	v_add_f32_e32 v2, v82, v2
	v_add_f32_e32 v2, v83, v2
	v_add_f32_e32 v2, v84, v2
	v_add_f32_e32 v2, v85, v2
	v_cvt_pk_bf16_f32 v156, v80, v81
	v_cvt_pk_bf16_f32 v157, v82, v83
	v_mfma_f32_32x32x16_bf16 v[96:111], v[188:191], v[140:143], v[48:63]
	ds_read_b64_tr_b16 v[188:189], v0 offset:28672
	ds_read_b64_tr_b16 v[190:191], v0 offset:29184
	v_add_f32_e32 v2, v86, v2
	v_add_f32_e32 v2, v87, v2
	v_add_f32_e32 v2, v88, v2
	v_add_f32_e32 v2, v89, v2
	v_cvt_pk_bf16_f32 v158, v84, v85
	v_cvt_pk_bf16_f32 v159, v86, v87
	v_mfma_f32_32x32x16_bf16 v[112:127], v[184:187], v[140:143], v[48:63]
	ds_read_b64_tr_b16 v[10:11], v0 offset:25600
	ds_read_b64_tr_b16 v[12:13], v0 offset:26112
	v_add_f32_e32 v2, v90, v2
	v_add_f32_e32 v2, v91, v2
	v_add_f32_e32 v2, v92, v2
	v_add_f32_e32 v2, v93, v2
	v_cvt_pk_bf16_f32 v152, v88, v89
	v_cvt_pk_bf16_f32 v153, v90, v91
	v_mfma_f32_32x32x16_bf16 v[96:111], v[180:183], v[136:139], v[96:111]
	ds_read_b64_tr_b16 v[180:181], v0 offset:29696
	ds_read_b64_tr_b16 v[182:183], v0 offset:30208
	v_add_f32_e32 v2, v94, v2
	v_add_f32_e32 v2, v95, v2
	v_add_f32_e32 v2, v64, v2
	v_add_f32_e32 v2, v65, v2
	v_cvt_pk_bf16_f32 v154, v92, v93
	v_cvt_pk_bf16_f32 v155, v94, v95
	v_mfma_f32_32x32x16_bf16 v[112:127], v[176:179], v[136:139], v[112:127]
	ds_read_b64_tr_b16 v[176:177], v0 offset:26624
	ds_read_b64_tr_b16 v[178:179], v0 offset:27136
	v_add_f32_e32 v2, v66, v2
	v_add_f32_e32 v2, v67, v2
	v_add_f32_e32 v2, v68, v2
	v_add_f32_e32 v6, v69, v2
	v_cvt_pk_bf16_f32 v148, v64, v65
	v_cvt_pk_bf16_f32 v149, v66, v67
	v_mfma_f32_32x32x16_bf16 v[96:111], v[172:175], v[132:135], v[96:111]
	ds_read_b64_tr_b16 v[2:3], v0 offset:30720
	ds_read_b64_tr_b16 v[4:5], v0 offset:31232
	v_add_f32_e32 v6, v70, v6
	v_add_f32_e32 v6, v71, v6
	v_add_f32_e32 v6, v72, v6
	v_add_f32_e32 v14, v73, v6
	v_cvt_pk_bf16_f32 v150, v68, v69
	v_cvt_pk_bf16_f32 v151, v70, v71
	v_mfma_f32_32x32x16_bf16 v[112:127], v[168:171], v[132:135], v[112:127]
	ds_read_b64_tr_b16 v[6:7], v0 offset:27648
	ds_read_b64_tr_b16 v[8:9], v0 offset:28160
	v_add_f32_e32 v14, v74, v14
	v_add_f32_e32 v14, v75, v14
	v_add_f32_e32 v14, v76, v14
	v_add_f32_e32 v14, v77, v14
	v_cvt_pk_bf16_f32 v144, v72, v73
	v_cvt_pk_bf16_f32 v145, v74, v75
	v_mfma_f32_32x32x16_bf16 v[96:111], v[164:167], v[128:131], v[96:111]
	ds_read_b64_tr_b16 v[164:165], v0 offset:31744
	ds_read_b64_tr_b16 v[166:167], v0 offset:32256
	v_add_f32_e32 v0, v78, v14
	v_add_f32_e32 v0, v79, v0
	v_add_f32_e32 v0, 0, v0
	v_cvt_pk_bf16_f32 v146, v76, v77
	v_cvt_pk_bf16_f32 v147, v78, v79
	v_mfma_f32_32x32x16_bf16 v[112:127], v[160:163], v[128:131], v[112:127]
	v_lshl_add_u64 v[14:15], v[202:203], 0, s[54:55]
	s_add_i32 s18, s69, s38
	s_mov_b32 s19, m0
	s_mov_b32 m0, s18
	s_nop 0
	global_load_lds_dwordx4 v[14:15], off
	s_mov_b32 m0, s19
	v_lshl_add_u64 v[14:15], v[200:201], 0, s[54:55]
	s_add_i32 s18, s7, s59
	s_mov_b32 s19, m0
	s_mov_b32 m0, s18
	s_nop 0
	global_load_lds_dwordx4 v[14:15], off
	s_mov_b32 m0, s19
	ds_read_b128 v[64:67], v204
	ds_read_b128 v[68:71], v204 offset:32
	ds_read_b128 v[72:75], v204 offset:128
	v_add_f32_e32 v0, v230, v0
	s_waitcnt lgkmcnt(2)
	v_pk_add_f32 v[82:83], v[98:99], v[66:67]
	s_waitcnt lgkmcnt(1)
	v_pk_add_f32 v[84:85], v[100:101], v[68:69]
	s_waitcnt lgkmcnt(0)
	v_pk_add_f32 v[14:15], v[112:113], v[72:73]
	v_pk_add_f32 v[66:67], v[114:115], v[74:75]
	ds_read_b128 v[72:75], v204 offset:160
	v_pk_add_f32 v[86:87], v[102:103], v[70:71]
	v_pk_add_f32 v[64:65], v[96:97], v[64:65]
	v_max3_f32 v81, v82, v83, v15
	v_max_f32_e32 v80, v64, v65
	s_waitcnt lgkmcnt(0)
	v_pk_add_f32 v[68:69], v[116:117], v[72:73]
	v_pk_add_f32 v[70:71], v[118:119], v[74:75]
	ds_read_b128 v[72:75], v204 offset:64
	ds_read_b128 v[76:79], v204 offset:192
	v_max3_f32 v80, v80, v14, v66
	v_max3_f32 v80, v80, v67, v84
	v_max3_f32 v81, v81, v86, v87
	s_waitcnt lgkmcnt(1)
	v_pk_add_f32 v[88:89], v[104:105], v[72:73]
	s_waitcnt lgkmcnt(0)
	v_pk_add_f32 v[72:73], v[120:121], v[76:77]
	v_pk_add_f32 v[90:91], v[106:107], v[74:75]
	v_pk_add_f32 v[74:75], v[122:123], v[78:79]
	ds_read_b128 v[76:79], v204 offset:96
	ds_read_b128 v[94:97], v204 offset:224
	v_max3_f32 v80, v80, v85, v68
	v_max3_f32 v81, v81, v70, v71
	v_max3_f32 v80, v80, v69, v88
	v_max3_f32 v81, v81, v90, v91
	s_waitcnt lgkmcnt(1)
	v_pk_add_f32 v[92:93], v[108:109], v[76:77]
	s_waitcnt lgkmcnt(0)
	v_pk_add_f32 v[76:77], v[124:125], v[94:95]
	v_pk_add_f32 v[94:95], v[110:111], v[78:79]
	v_max3_f32 v80, v80, v89, v72
	v_max3_f32 v81, v81, v74, v75
	v_pk_add_f32 v[78:79], v[126:127], v[96:97]
	v_max3_f32 v80, v80, v73, v92
	v_max3_f32 v81, v81, v94, v95
	v_max3_f32 v80, v80, v93, v76
	v_max3_f32 v81, v81, v78, v79
	v_max3_f32 v80, v80, v77, v81
	v_mov_b32_e32 v81, v80
	s_nop 1
	v_permlane32_swap_b32_e32 v80, v81
	v_max_f32_e32 v81, v81, v81
	v_max_f32_e32 v80, v80, v80
	v_max_f32_e32 v80, v80, v81
	v_cmp_lt_f32_e32 vcc, s96, v80
	s_cmp_lg_u64 vcc, 0
	s_cselect_b64 s[18:19], -1, 0
	s_cbranch_vccnz .LBB0_259

.LBB0_254:
	s_add_i32 s18, s7, 0x2000
	s_cmpk_lg_i32 s7, 0x4000
	s_cselect_b32 s60, s18, 0
	v_add_u32_e32 v14, s69, v225
	ds_read_b64_tr_b16 v[168:169], v14 offset:24576
	ds_read_b64_tr_b16 v[170:171], v14 offset:25088
	v_add_f32_e32 v2, v80, v81
	v_add_f32_e32 v2, v82, v2
	v_add_f32_e32 v2, v83, v2
	v_add_f32_e32 v2, v84, v2
	v_add_f32_e32 v2, v85, v2
	v_cvt_pk_bf16_f32 v156, v80, v81
	v_cvt_pk_bf16_f32 v157, v82, v83
	v_mfma_f32_32x32x16_bf16 v[96:111], v[112:115], v[140:143], v[48:63]
	ds_read_b64_tr_b16 v[164:165], v14 offset:28672
	ds_read_b64_tr_b16 v[166:167], v14 offset:29184
	v_add_f32_e32 v2, v86, v2
	v_add_f32_e32 v2, v87, v2
	v_add_f32_e32 v2, v88, v2
	v_add_f32_e32 v2, v89, v2
	v_cvt_pk_bf16_f32 v158, v84, v85
	v_cvt_pk_bf16_f32 v159, v86, v87
	v_mfma_f32_32x32x16_bf16 v[112:127], v[160:163], v[140:143], v[48:63]
	ds_read_b64_tr_b16 v[10:11], v14 offset:25600
	ds_read_b64_tr_b16 v[12:13], v14 offset:26112
	v_add_f32_e32 v2, v90, v2
	v_add_f32_e32 v2, v91, v2
	v_add_f32_e32 v2, v92, v2
	v_add_f32_e32 v2, v93, v2
	v_cvt_pk_bf16_f32 v152, v88, v89
	v_cvt_pk_bf16_f32 v153, v90, v91
	v_mfma_f32_32x32x16_bf16 v[96:111], v[192:195], v[136:139], v[96:111]
	ds_read_b64_tr_b16 v[160:161], v14 offset:29696
	ds_read_b64_tr_b16 v[162:163], v14 offset:30208
	v_add_f32_e32 v2, v94, v2
	v_add_f32_e32 v2, v95, v2
	v_add_f32_e32 v2, v64, v2
	v_add_f32_e32 v2, v65, v2
	v_cvt_pk_bf16_f32 v154, v92, v93
	v_cvt_pk_bf16_f32 v155, v94, v95
	v_mfma_f32_32x32x16_bf16 v[112:127], v[188:191], v[136:139], v[112:127]
	ds_read_b64_tr_b16 v[196:197], v14 offset:26624
	ds_read_b64_tr_b16 v[198:199], v14 offset:27136
	v_add_f32_e32 v2, v66, v2
	v_add_f32_e32 v2, v67, v2
	v_add_f32_e32 v2, v68, v2
	v_add_f32_e32 v6, v69, v2
	v_cvt_pk_bf16_f32 v148, v64, v65
	v_cvt_pk_bf16_f32 v149, v66, v67
	v_mfma_f32_32x32x16_bf16 v[96:111], v[184:187], v[132:135], v[96:111]
	ds_read_b64_tr_b16 v[2:3], v14 offset:30720
	ds_read_b64_tr_b16 v[4:5], v14 offset:31232
	v_add_f32_e32 v6, v70, v6
	v_add_f32_e32 v6, v71, v6
	v_add_f32_e32 v6, v72, v6
	v_add_f32_e32 v15, v73, v6
	v_cvt_pk_bf16_f32 v150, v68, v69
	v_cvt_pk_bf16_f32 v151, v70, v71
	v_mfma_f32_32x32x16_bf16 v[112:127], v[180:183], v[132:135], v[112:127]
	ds_read_b64_tr_b16 v[6:7], v14 offset:27648
	ds_read_b64_tr_b16 v[8:9], v14 offset:28160
	v_add_f32_e32 v15, v74, v15
	v_add_f32_e32 v15, v75, v15
	v_add_f32_e32 v15, v76, v15
	v_add_f32_e32 v15, v77, v15
	v_cvt_pk_bf16_f32 v144, v72, v73
	v_cvt_pk_bf16_f32 v145, v74, v75
	v_mfma_f32_32x32x16_bf16 v[96:111], v[176:179], v[128:131], v[96:111]
	ds_read_b64_tr_b16 v[192:193], v14 offset:31744
	ds_read_b64_tr_b16 v[194:195], v14 offset:32256
	v_add_f32_e32 v14, v78, v15
	v_add_f32_e32 v14, v79, v14
	v_add_f32_e32 v80, 0, v14
	v_cvt_pk_bf16_f32 v146, v76, v77
	v_cvt_pk_bf16_f32 v147, v78, v79
	v_mfma_f32_32x32x16_bf16 v[112:127], v[172:175], v[128:131], v[112:127]
	s_add_i32 s18, s7, s38
	s_mov_b32 s19, m0
	s_mov_b32 m0, s18
	s_nop 0
	global_load_lds_dwordx4 v[202:203], off
	s_mov_b32 m0, s19
	s_add_i32 s18, s60, s59
	s_mov_b32 s19, m0
	s_mov_b32 m0, s18
	s_nop 0
	global_load_lds_dwordx4 v[200:201], off
	s_mov_b32 m0, s19
	ds_read_b128 v[64:67], v204 offset:256
	ds_read_b128 v[68:71], v204 offset:288
	ds_read_b128 v[72:75], v204 offset:384
	v_add_f32_e32 v230, v0, v80
	s_waitcnt lgkmcnt(2)
	v_pk_add_f32 v[82:83], v[98:99], v[66:67]
	s_waitcnt lgkmcnt(1)
	v_pk_add_f32 v[84:85], v[100:101], v[68:69]
	s_waitcnt lgkmcnt(0)
	s_nop 0
	v_pk_add_f32 v[14:15], v[112:113], v[72:73]
	v_pk_add_f32 v[66:67], v[114:115], v[74:75]
	ds_read_b128 v[72:75], v204 offset:416
	v_pk_add_f32 v[86:87], v[102:103], v[70:71]
	v_pk_add_f32 v[64:65], v[96:97], v[64:65]
	s_waitcnt lgkmcnt(0)
	v_pk_add_f32 v[68:69], v[116:117], v[72:73]
	v_pk_add_f32 v[70:71], v[118:119], v[74:75]
	ds_read_b128 v[72:75], v204 offset:320
	ds_read_b128 v[76:79], v204 offset:448
	v_max_f32_e32 v81, v64, v65
	v_max3_f32 v81, v81, v14, v66
	v_max3_f32 v81, v81, v67, v84
	s_waitcnt lgkmcnt(1)
	v_pk_add_f32 v[88:89], v[104:105], v[72:73]
	s_waitcnt lgkmcnt(0)
	v_pk_add_f32 v[72:73], v[120:121], v[76:77]
	v_pk_add_f32 v[90:91], v[106:107], v[74:75]
	v_pk_add_f32 v[74:75], v[122:123], v[78:79]
	ds_read_b128 v[76:79], v204 offset:352
	ds_read_b128 v[94:97], v204 offset:480
	v_max3_f32 v81, v81, v85, v68
	v_max3_f32 v81, v81, v69, v88
	v_max3_f32 v81, v81, v89, v72
	s_waitcnt lgkmcnt(1)
	v_pk_add_f32 v[92:93], v[108:109], v[76:77]
	s_waitcnt lgkmcnt(0)
	v_pk_add_f32 v[76:77], v[124:125], v[94:95]
	v_pk_add_f32 v[94:95], v[110:111], v[78:79]
	v_pk_add_f32 v[78:79], v[126:127], v[96:97]
	v_max3_f32 v96, v82, v83, v15
	v_max3_f32 v96, v96, v86, v87
	v_max3_f32 v96, v96, v70, v71
	v_max3_f32 v96, v96, v90, v91
	v_max3_f32 v96, v96, v74, v75
	v_max3_f32 v81, v81, v73, v92
	v_max3_f32 v96, v96, v94, v95
	v_max3_f32 v81, v81, v93, v76
	v_max3_f32 v96, v96, v78, v79
	v_max3_f32 v0, v81, v77, v96
	v_mov_b32_e32 v80, v0
	s_nop 1
	v_permlane32_swap_b32_e32 v0, v80
	v_max_f32_e32 v80, v80, v80
	v_max_f32_e32 v0, v0, v0
	v_max_f32_e32 v0, v0, v80
	v_cmp_lt_f32_e32 vcc, s96, v0
	s_cmp_lg_u64 vcc, 0
	s_cselect_b64 s[18:19], -1, 0
	s_cbranch_vccnz .LBB0_262
